# grid barrier after the last layer's phase_f skipped for the first sequence half too (phase_n of the second half shares no data with it)
# speedup vs baseline: 1.0087x; 1.0043x over previous
; DI void xcd_barrier(const XcdBarrier& b) {
;     asm volatile("s_waitcnt vmcnt(0)" ::: "memory");
;     __syncthreads();
;     if (threadIdx.x == 0) {
;         unsigned* bar = b.bar;
;         __builtin_amdgcn_s_waitcnt(0);
;         unsigned nloc = b.st[0], nx = b.st[1];
;         if (nloc == 0u) { xcd_barrier_complete(bar, b.x, nloc, nx); b.st[0] = nloc; b.st[1] = nx; }
; __global__ void __launch_bounds__(512, 1) mega(Params P) {
;     ...
;             if (!(hb == 1 && l == 1)) xcd_barrier(xb);
.LBB0_452:
	s_or_b64 exec, exec, s[0:1]
	v_readlane_b32 s0, v236, 18
	v_readlane_b32 s2, v236, 44
	v_readlane_b32 s1, v236, 19
	v_readlane_b32 s3, v236, 45
	s_mov_b64 s[0:1], s[2:3]
	s_and_b64 vcc, exec, s[0:1]
	s_cbranch_vccnz .LBB0_129
	s_waitcnt vmcnt(0)
	s_waitcnt lgkmcnt(0)
	s_barrier
	s_and_saveexec_b64 s[0:1], s[64:65]
	s_cbranch_execz .LBB0_128
	v_mov_b32_e32 v0, s63
	s_waitcnt vmcnt(0) expcnt(0) lgkmcnt(0)
	ds_read_b32 v3, v0
	v_mov_b32_e32 v0, s70
	ds_read_b32 v2, v0
	s_waitcnt lgkmcnt(1)
	v_cmp_ne_u32_e32 vcc, 0, v3
	s_cbranch_vccnz .LBB0_469
	s_mov_b32 s2, 1
	s_branch .LBB0_457
